# one static s_setprio 1 at entry for the first-residency blocks (blockIdx < 256): the two blocks sharing a CU desynchronise
# baseline (speedup 1.0000x reference)
; #define LAS __attribute__((address_space(3)))
; __device__ __forceinline__ unsigned xb_add(unsigned* p, unsigned v) { return __hip_atomic_fetch_add(p, v, __ATOMIC_RELAXED, __HIP_MEMORY_SCOPE_AGENT); }
; __device__ __forceinline__ unsigned xb_xcc_id() { return (unsigned)__builtin_amdgcn_s_getreg((3 << 11) | 20) & 0xFu; }
; __device__ __forceinline__ XcdBarrier xcd_barrier_post(unsigned* bar, volatile LAS unsigned* st) {
;   XcdBarrier b; b.bar = bar; b.x = xb_xcc_id(); b.st = st;
;   if (threadIdx.x == 0) (void)xb_add(&bar[XB_XCNT(b.x)], 1u);
;   return b;
; __global__ void __launch_bounds__(256, 2) fwd_megakernel(Params p) {
;   extern __shared__ __attribute__((aligned(16))) char smem[];
;   cg::grid_group grid = cg::this_grid();
;   volatile LAS unsigned* st = (volatile LAS unsigned*)(smem + AUX_OFF + 768);
;   if (threadIdx.x < 2) st[threadIdx.x] = 0u;
;   __syncthreads();
;   XcdBarrier xb = xcd_barrier_post(p.bar, st);
_Z14fwd_megakernel6Params:
	s_cmp_lt_u32 s2, 0x100
	s_cbranch_scc0 .Lprio_skip
	s_setprio 1
.Lprio_skip:
	s_load_dword s3, s[0:1], 0x150
	s_load_dwordx2 s[4:5], s[0:1], 0x148
	s_load_dwordx16 s[68:83], s[0:1], 0x100
	s_add_u32 s6, s0, 0x148
	s_addc_u32 s7, s1, 0
	s_waitcnt lgkmcnt(0)
	v_writelane_b32 v240, s3, 0
	v_writelane_b32 v240, s4, 1
	v_and_b32_e32 v128, 0x3ff, v0
	v_cmp_gt_u32_e32 vcc, 2, v128
	v_writelane_b32 v240, s5, 2
	v_writelane_b32 v240, s6, 3
	v_lshl_add_u32 v131, v128, 2, 0
	s_nop 0
	v_writelane_b32 v240, s7, 4
	s_and_saveexec_b64 s[6:7], vcc
	v_add_u32_e32 v1, 0x10300, v131
	v_mov_b32_e32 v2, 0
	ds_write_b32 v1, v2
	s_or_b64 exec, exec, s[6:7]
	s_load_dword s6, s[0:1], 0x140
	s_waitcnt lgkmcnt(0)
	s_barrier
	s_getreg_b32 s3, hwreg(HW_REG_XCC_ID, 0, 4)
	s_and_b32 s3, s3, 15
	v_cmp_eq_u32_e64 s[34:35], 0, v128
	v_writelane_b32 v240, s3, 5
	s_and_saveexec_b64 s[10:11], s[34:35]
	s_cbranch_execz .LBB0_5
	s_mov_b64 s[4:5], exec
	v_mbcnt_lo_u32_b32 v1, s4, 0
	v_mbcnt_hi_u32_b32 v1, s5, v1
	v_cmp_eq_u32_e32 vcc, 0, v1
	s_and_b64 s[8:9], exec, vcc
	s_mov_b64 exec, s[8:9]
	s_cbranch_execz .LBB0_5
	v_readlane_b32 s3, v240, 5
	s_lshl_b32 s7, s3, 8
	s_bcnt1_i32_b64 s4, s[4:5]
	v_mov_b32_e32 v1, s7
	v_mov_b32_e32 v2, s4
	global_atomic_add v1, v2, s[82:83] offset:1024
